# the eight GEMM K-loop heads aligned to 64 bytes (.p2align 6, s_nop padding executed once per tile); on v092
# speedup vs baseline: 1.0047x; 1.0047x over previous
.Lk1_w4j:
	s_barrier
	v_mfma_f32_16x16x32_bf16 v[52:55], v[208:211], v[172:175], 0
	v_mfma_f32_16x16x32_bf16 v[48:51], v[216:219], v[172:175], 0
	v_mfma_f32_16x16x32_bf16 v[36:39], v[208:211], v[180:183], 0
	v_mfma_f32_16x16x32_bf16 v[32:35], v[216:219], v[180:183], 0
	v_mfma_f32_16x16x32_bf16 v[20:23], v[208:211], v[188:191], 0
	v_mfma_f32_16x16x32_bf16 v[16:19], v[216:219], v[188:191], 0
	v_mfma_f32_16x16x32_bf16 v[4:7], v[208:211], v[200:203], 0
	v_mfma_f32_16x16x32_bf16 v[0:3], v[216:219], v[200:203], 0
	v_mfma_f32_16x16x32_bf16 v[52:55], v[212:215], v[176:179], v[52:55]
	v_mfma_f32_16x16x32_bf16 v[48:51], v[220:223], v[176:179], v[48:51]
	v_mfma_f32_16x16x32_bf16 v[36:39], v[212:215], v[184:187], v[36:39]
	v_mfma_f32_16x16x32_bf16 v[32:35], v[220:223], v[184:187], v[32:35]
	v_mfma_f32_16x16x32_bf16 v[20:23], v[212:215], v[196:199], v[20:23]
	v_mfma_f32_16x16x32_bf16 v[16:19], v[220:223], v[196:199], v[16:19]
	v_mfma_f32_16x16x32_bf16 v[4:7], v[212:215], v[204:207], v[4:7]
	v_mfma_f32_16x16x32_bf16 v[0:3], v[220:223], v[204:207], v[0:3]
	s_add_i32 s93, 0, 0x18000
	v_add_u32_e32 v136, s93, v158
	s_barrier
	ds_read_b128 v[148:151], v136
	ds_read_b128 v[152:155], v136 offset:1024
	ds_read_b128 v[164:167], v136 offset:2048
	ds_read_b128 v[168:171], v136 offset:3072
	s_add_u32 s54, s54, 0x40000
	s_addc_u32 s55, s55, 0
	s_mov_b32 m0, s60
	v_lshl_add_u64 v[208:209], s[54:55], 0, v[128:129]
	ds_read_b128 v[172:175], v160 offset:32768
	ds_read_b128 v[176:179], v160 offset:33792
	ds_read_b128 v[180:183], v160 offset:34816
	ds_read_b128 v[184:187], v160 offset:35840
	ds_read_b128 v[188:191], v160 offset:36864
	ds_read_b128 v[196:199], v160 offset:37888
	ds_read_b128 v[200:203], v160 offset:38912
	ds_read_b128 v[204:207], v160 offset:39936
	global_load_lds_dwordx4 v[208:209], off
	v_lshl_add_u64 v[208:209], s[54:55], 0, v[132:133]
	s_mov_b32 m0, s61
	s_nop 0
	global_load_lds_dwordx4 v[208:209], off
	s_waitcnt lgkmcnt(8)
	s_barrier
	s_waitcnt lgkmcnt(0)
	v_mfma_f32_16x16x32_bf16 v[124:127], v[148:151], v[172:175], v[124:127]
	v_mfma_f32_16x16x32_bf16 v[120:123], v[164:167], v[172:175], v[120:123]
	v_mfma_f32_16x16x32_bf16 v[108:111], v[148:151], v[180:183], v[108:111]
	v_mfma_f32_16x16x32_bf16 v[104:107], v[164:167], v[180:183], v[104:107]
	v_mfma_f32_16x16x32_bf16 v[92:95], v[148:151], v[188:191], v[92:95]
	v_mfma_f32_16x16x32_bf16 v[88:91], v[164:167], v[188:191], v[88:91]
	v_mfma_f32_16x16x32_bf16 v[76:79], v[148:151], v[200:203], v[76:79]
	v_mfma_f32_16x16x32_bf16 v[72:75], v[164:167], v[200:203], v[72:75]
	v_mfma_f32_16x16x32_bf16 v[124:127], v[152:155], v[176:179], v[124:127]
	v_mfma_f32_16x16x32_bf16 v[120:123], v[168:171], v[176:179], v[120:123]
	v_mfma_f32_16x16x32_bf16 v[108:111], v[152:155], v[184:187], v[108:111]
	v_mfma_f32_16x16x32_bf16 v[104:107], v[168:171], v[184:187], v[104:107]
	v_mfma_f32_16x16x32_bf16 v[92:95], v[152:155], v[196:199], v[92:95]
	v_mfma_f32_16x16x32_bf16 v[88:91], v[168:171], v[196:199], v[88:91]
	v_mfma_f32_16x16x32_bf16 v[76:79], v[152:155], v[204:207], v[76:79]
	v_mfma_f32_16x16x32_bf16 v[72:75], v[168:171], v[204:207], v[72:75]
	s_barrier
	s_add_i32 s54, 0, 0x1c000
	s_add_i32 s55, s93, s57
	v_add_u32_e32 v136, s54, v158
	v_lshl_add_u64 v[156:157], v[156:157], 0, s[0:1]
	s_mov_b32 m0, s55
	ds_read_b128 v[208:211], v136
	ds_read_b128 v[212:215], v136 offset:1024
	ds_read_b128 v[216:219], v136 offset:2048
	ds_read_b128 v[220:223], v136 offset:3072
	global_load_lds_dwordx4 v[156:157], off
	v_lshl_add_u64 v[156:157], v[224:225], 0, s[0:1]
	s_add_i32 m0, s55, 0x2000
	s_nop 0
	global_load_lds_dwordx4 v[156:157], off
	s_barrier
	s_waitcnt lgkmcnt(0)
	v_mfma_f32_16x16x32_bf16 v[116:119], v[208:211], v[172:175], v[116:119]
	v_mfma_f32_16x16x32_bf16 v[112:115], v[216:219], v[172:175], v[112:115]
	v_mfma_f32_16x16x32_bf16 v[100:103], v[208:211], v[180:183], v[100:103]
	v_mfma_f32_16x16x32_bf16 v[96:99], v[216:219], v[180:183], v[96:99]
	v_mfma_f32_16x16x32_bf16 v[84:87], v[208:211], v[188:191], v[84:87]
	v_mfma_f32_16x16x32_bf16 v[80:83], v[216:219], v[188:191], v[80:83]
	v_mfma_f32_16x16x32_bf16 v[68:71], v[208:211], v[200:203], v[68:71]
	v_mfma_f32_16x16x32_bf16 v[64:67], v[216:219], v[200:203], v[64:67]
	v_mfma_f32_16x16x32_bf16 v[116:119], v[212:215], v[176:179], v[116:119]
	v_mfma_f32_16x16x32_bf16 v[112:115], v[220:223], v[176:179], v[112:115]
	v_mfma_f32_16x16x32_bf16 v[100:103], v[212:215], v[184:187], v[100:103]
	v_mfma_f32_16x16x32_bf16 v[96:99], v[220:223], v[184:187], v[96:99]
	v_mfma_f32_16x16x32_bf16 v[84:87], v[212:215], v[196:199], v[84:87]
	v_mfma_f32_16x16x32_bf16 v[80:83], v[220:223], v[196:199], v[80:83]
	v_mfma_f32_16x16x32_bf16 v[68:71], v[212:215], v[204:207], v[68:71]
	v_mfma_f32_16x16x32_bf16 v[64:67], v[220:223], v[204:207], v[64:67]
	s_mov_b32 m0, s65
	v_lshl_add_u64 v[156:157], v[226:227], 0, s[0:1]
	s_waitcnt vmcnt(10)
	s_barrier
	ds_read_b128 v[172:175], v160 offset:49152
	ds_read_b128 v[176:179], v160 offset:50176
	ds_read_b128 v[180:183], v160 offset:51200
	ds_read_b128 v[184:187], v160 offset:52224
	ds_read_b128 v[188:191], v160 offset:53248
	ds_read_b128 v[196:199], v160 offset:54272
	ds_read_b128 v[200:203], v160 offset:55296
	ds_read_b128 v[204:207], v160 offset:56320
	global_load_lds_dwordx4 v[156:157], off
	v_lshl_add_u64 v[156:157], v[228:229], 0, s[0:1]
	s_mov_b32 m0, s66
	s_nop 0
	global_load_lds_dwordx4 v[156:157], off
	s_barrier
	s_waitcnt lgkmcnt(0)
	v_mfma_f32_16x16x32_bf16 v[60:63], v[148:151], v[172:175], v[60:63]
	v_mfma_f32_16x16x32_bf16 v[56:59], v[164:167], v[172:175], v[56:59]
	v_mfma_f32_16x16x32_bf16 v[44:47], v[148:151], v[180:183], v[44:47]
	v_mfma_f32_16x16x32_bf16 v[40:43], v[164:167], v[180:183], v[40:43]
	v_mfma_f32_16x16x32_bf16 v[28:31], v[148:151], v[188:191], v[28:31]
	v_mfma_f32_16x16x32_bf16 v[24:27], v[164:167], v[188:191], v[24:27]
	v_mfma_f32_16x16x32_bf16 v[12:15], v[148:151], v[200:203], v[12:15]
	v_mfma_f32_16x16x32_bf16 v[8:11], v[164:167], v[200:203], v[8:11]
	v_mfma_f32_16x16x32_bf16 v[60:63], v[152:155], v[176:179], v[60:63]
	v_mfma_f32_16x16x32_bf16 v[56:59], v[168:171], v[176:179], v[56:59]
	v_mfma_f32_16x16x32_bf16 v[44:47], v[152:155], v[184:187], v[44:47]
	v_mfma_f32_16x16x32_bf16 v[40:43], v[168:171], v[184:187], v[40:43]
	v_mfma_f32_16x16x32_bf16 v[28:31], v[152:155], v[196:199], v[28:31]
	v_mfma_f32_16x16x32_bf16 v[24:27], v[168:171], v[196:199], v[24:27]
	v_mfma_f32_16x16x32_bf16 v[12:15], v[152:155], v[204:207], v[12:15]
	v_mfma_f32_16x16x32_bf16 v[8:11], v[168:171], v[204:207], v[8:11]
	s_barrier
	s_add_u32 s52, s52, 0x10080
	s_addc_u32 s53, s53, 0
	s_add_i32 s54, s54, s57
	v_lshl_add_u64 v[148:149], s[52:53], 0, v[130:131]
	s_mov_b32 m0, s54
	s_nop 0
	global_load_lds_dwordx4 v[148:149], off
	v_lshl_add_u64 v[148:149], s[52:53], 0, v[134:135]
	s_add_i32 m0, s54, 0x2000
	s_nop 0
	global_load_lds_dwordx4 v[148:149], off
	s_waitcnt vmcnt(6)
	s_barrier
	v_mfma_f32_16x16x32_bf16 v[52:55], v[208:211], v[172:175], v[52:55]
	v_mfma_f32_16x16x32_bf16 v[48:51], v[216:219], v[172:175], v[48:51]
	v_mfma_f32_16x16x32_bf16 v[36:39], v[208:211], v[180:183], v[36:39]
	v_mfma_f32_16x16x32_bf16 v[32:35], v[216:219], v[180:183], v[32:35]
	v_mfma_f32_16x16x32_bf16 v[20:23], v[208:211], v[188:191], v[20:23]
	v_mfma_f32_16x16x32_bf16 v[16:19], v[216:219], v[188:191], v[16:19]
	v_mfma_f32_16x16x32_bf16 v[4:7], v[208:211], v[200:203], v[4:7]
	v_mfma_f32_16x16x32_bf16 v[0:3], v[216:219], v[200:203], v[0:3]
	v_mfma_f32_16x16x32_bf16 v[52:55], v[212:215], v[176:179], v[52:55]
	v_mfma_f32_16x16x32_bf16 v[48:51], v[220:223], v[176:179], v[48:51]
	v_mfma_f32_16x16x32_bf16 v[36:39], v[212:215], v[184:187], v[36:39]
	v_mfma_f32_16x16x32_bf16 v[32:35], v[220:223], v[184:187], v[32:35]
	v_mfma_f32_16x16x32_bf16 v[20:23], v[212:215], v[196:199], v[20:23]
	v_mfma_f32_16x16x32_bf16 v[16:19], v[220:223], v[196:199], v[16:19]
	v_mfma_f32_16x16x32_bf16 v[4:7], v[212:215], v[204:207], v[4:7]
	v_mfma_f32_16x16x32_bf16 v[0:3], v[220:223], v[204:207], v[0:3]
	s_add_i32 s92, s92, 2
	s_add_u32 s50, s50, 0x100
	s_addc_u32 s51, s51, 0
	s_add_u32 s45, s45, 0x100
	s_addc_u32 s91, s91, 0
	s_cmp_gt_u32 s92, 13
	s_barrier
	s_cbranch_scc0 .LBB0_178
	.p2align	6

.LBB0_341:
	s_ashr_i32 s9, s8, 31
	v_cmp_lt_i64_e64 s[48:49], s[10:11], 64
	s_lshl_b64 s[10:11], s[8:9], 19
	s_add_u32 s10, s82, s10
	s_addc_u32 s11, s83, s11
	s_and_b64 s[12:13], s[48:49], exec
	s_cselect_b32 s9, s11, s45
	s_cselect_b32 s63, s10, s44
	s_ashr_i32 s7, s6, 31
	s_lshl_b64 s[12:13], s[6:7], 19
	s_add_u32 s12, s80, s12
	s_addc_u32 s13, s81, s13
	s_and_b64 s[48:49], s[48:49], exec
	s_cselect_b32 s7, s13, s47
	s_cselect_b32 s64, s12, s46
	s_add_u32 s44, s44, 0x40080
	s_addc_u32 s45, s45, 0
	s_add_u32 s65, s46, 0x100
	v_mov_b32_e32 v0, 0
	s_addc_u32 s66, s47, 0
	s_mov_b32 s67, -2
	v_mov_b64_e32 v[0:1], 0
	v_mov_b64_e32 v[2:3], 0
	v_mov_b64_e32 v[4:5], 0
	v_mov_b64_e32 v[6:7], 0
	v_mov_b64_e32 v[8:9], 0
	v_mov_b64_e32 v[10:11], 0
	v_mov_b64_e32 v[12:13], 0
	v_mov_b64_e32 v[14:15], 0
	v_mov_b64_e32 v[16:17], 0
	v_mov_b64_e32 v[18:19], 0
	v_mov_b64_e32 v[20:21], 0
	v_mov_b64_e32 v[22:23], 0
	v_mov_b64_e32 v[24:25], 0
	v_mov_b64_e32 v[26:27], 0
	v_mov_b64_e32 v[28:29], 0
	v_mov_b64_e32 v[30:31], 0
	v_mov_b64_e32 v[32:33], 0
	v_mov_b64_e32 v[34:35], 0
	v_mov_b64_e32 v[36:37], 0
	v_mov_b64_e32 v[38:39], 0
	v_mov_b64_e32 v[40:41], 0
	v_mov_b64_e32 v[42:43], 0
	v_mov_b64_e32 v[44:45], 0
	v_mov_b64_e32 v[46:47], 0
	v_mov_b64_e32 v[48:49], 0
	v_mov_b64_e32 v[50:51], 0
	v_mov_b64_e32 v[52:53], 0
	v_mov_b64_e32 v[54:55], 0
	v_mov_b64_e32 v[56:57], 0
	v_mov_b64_e32 v[58:59], 0
	v_mov_b64_e32 v[60:61], 0
	v_mov_b64_e32 v[62:63], 0
	v_mov_b64_e32 v[64:65], 0
	v_mov_b64_e32 v[66:67], 0
	v_mov_b64_e32 v[68:69], 0
	v_mov_b64_e32 v[70:71], 0
	v_mov_b64_e32 v[72:73], 0
	v_mov_b64_e32 v[74:75], 0
	v_mov_b64_e32 v[76:77], 0
	v_mov_b64_e32 v[78:79], 0
	v_mov_b64_e32 v[80:81], 0
	v_mov_b64_e32 v[82:83], 0
	v_mov_b64_e32 v[84:85], 0
	v_mov_b64_e32 v[86:87], 0
	v_mov_b64_e32 v[88:89], 0
	v_mov_b64_e32 v[90:91], 0
	v_mov_b64_e32 v[92:93], 0
	v_mov_b64_e32 v[94:95], 0
	v_mov_b64_e32 v[96:97], 0
	v_mov_b64_e32 v[98:99], 0
	v_mov_b64_e32 v[100:101], 0
	v_mov_b64_e32 v[102:103], 0
	v_mov_b64_e32 v[104:105], 0
	v_mov_b64_e32 v[106:107], 0
	v_mov_b64_e32 v[108:109], 0
	v_mov_b64_e32 v[110:111], 0
	v_mov_b64_e32 v[112:113], 0
	v_mov_b64_e32 v[114:115], 0
	v_mov_b64_e32 v[116:117], 0
	v_mov_b64_e32 v[118:119], 0
	v_mov_b64_e32 v[120:121], 0
	v_mov_b64_e32 v[122:123], 0
	v_mov_b64_e32 v[124:125], 0
	v_mov_b64_e32 v[126:127], 0
	.p2align	6

.LBB0_667:
	s_add_u32 s56, s52, s54
	s_addc_u32 s57, s53, s55
	s_add_u32 s56, s56, 0x100
	s_addc_u32 s57, s57, 0
	s_add_u32 vcc_lo, s96, s54
	s_addc_u32 vcc_hi, s97, s55
	s_cmpk_eq_i32 s54, 0x700
	s_cselect_b32 s59, s47, s57
	s_cselect_b32 s58, s94, s56
	s_cselect_b32 s57, s45, vcc_hi
	s_cselect_b32 s56, s95, vcc_lo
	s_add_i32 vcc_lo, 0, 0x10000
	v_add_u32_e32 v1, vcc_lo, v196
	ds_read_b128 v[132:135], v1
	ds_read_b128 v[136:139], v1 offset:1024
	ds_read_b128 v[140:143], v1 offset:2048
	ds_read_b128 v[144:147], v1 offset:3072
	v_lshl_add_u64 v[2:3], v[188:189], 0, s[54:55]
	s_add_i32 m0, s63, 0xc000
	ds_read_b128 v[148:151], v199
	ds_read_b128 v[152:155], v199 offset:1024
	ds_read_b128 v[156:159], v199 offset:2048
	ds_read_b128 v[160:163], v199 offset:3072
	ds_read_b128 v[164:167], v199 offset:4096
	ds_read_b128 v[200:203], v199 offset:5120
	ds_read_b128 v[204:207], v199 offset:6144
	ds_read_b128 v[208:211], v199 offset:7168
	global_load_lds_dwordx4 v[2:3], off
	v_lshl_add_u64 v[2:3], v[190:191], 0, s[54:55]
	s_add_i32 m0, s63, 0xe000
	s_nop 0
	global_load_lds_dwordx4 v[2:3], off
	s_waitcnt lgkmcnt(8)
	s_barrier
	s_waitcnt lgkmcnt(0)
	v_mfma_f32_16x16x32_bf16 v[128:131], v[132:135], v[148:151], v[128:131]
	v_mfma_f32_16x16x32_bf16 v[124:127], v[140:143], v[148:151], v[124:127]
	v_mfma_f32_16x16x32_bf16 v[112:115], v[132:135], v[156:159], v[112:115]
	v_mfma_f32_16x16x32_bf16 v[108:111], v[140:143], v[156:159], v[108:111]
	v_mfma_f32_16x16x32_bf16 v[96:99], v[132:135], v[164:167], v[96:99]
	v_mfma_f32_16x16x32_bf16 v[92:95], v[140:143], v[164:167], v[92:95]
	v_mfma_f32_16x16x32_bf16 v[80:83], v[132:135], v[204:207], v[80:83]
	v_mfma_f32_16x16x32_bf16 v[76:79], v[140:143], v[204:207], v[76:79]
	v_mfma_f32_16x16x32_bf16 v[128:131], v[136:139], v[152:155], v[128:131]
	v_mfma_f32_16x16x32_bf16 v[124:127], v[144:147], v[152:155], v[124:127]
	v_mfma_f32_16x16x32_bf16 v[112:115], v[136:139], v[160:163], v[112:115]
	v_mfma_f32_16x16x32_bf16 v[108:111], v[144:147], v[160:163], v[108:111]
	v_mfma_f32_16x16x32_bf16 v[96:99], v[136:139], v[200:203], v[96:99]
	v_mfma_f32_16x16x32_bf16 v[92:95], v[144:147], v[200:203], v[92:95]
	v_mfma_f32_16x16x32_bf16 v[80:83], v[136:139], v[208:211], v[80:83]
	v_mfma_f32_16x16x32_bf16 v[76:79], v[144:147], v[208:211], v[76:79]
	s_barrier
	s_add_i32 vcc_lo, vcc_lo, s61
	v_add_u32_e32 v1, s93, v196
	v_lshl_add_u64 v[228:229], s[56:57], 0, v[172:173]
	s_mov_b32 m0, vcc_lo
	ds_read_b128 v[212:215], v1
	ds_read_b128 v[216:219], v1 offset:1024
	ds_read_b128 v[220:223], v1 offset:2048
	ds_read_b128 v[224:227], v1 offset:3072
	global_load_lds_dwordx4 v[228:229], off
	v_lshl_add_u64 v[230:231], s[56:57], 0, v[168:169]
	s_add_i32 m0, vcc_lo, 0x2000
	s_nop 0
	global_load_lds_dwordx4 v[230:231], off
	s_barrier
	s_waitcnt lgkmcnt(0)
	v_mfma_f32_16x16x32_bf16 v[120:123], v[212:215], v[148:151], v[120:123]
	v_mfma_f32_16x16x32_bf16 v[116:119], v[220:223], v[148:151], v[116:119]
	v_mfma_f32_16x16x32_bf16 v[104:107], v[212:215], v[156:159], v[104:107]
	v_mfma_f32_16x16x32_bf16 v[100:103], v[220:223], v[156:159], v[100:103]
	v_mfma_f32_16x16x32_bf16 v[88:91], v[212:215], v[164:167], v[88:91]
	v_mfma_f32_16x16x32_bf16 v[84:87], v[220:223], v[164:167], v[84:87]
	v_mfma_f32_16x16x32_bf16 v[72:75], v[212:215], v[204:207], v[72:75]
	v_mfma_f32_16x16x32_bf16 v[68:71], v[220:223], v[204:207], v[68:71]
	v_mfma_f32_16x16x32_bf16 v[120:123], v[216:219], v[152:155], v[120:123]
	v_mfma_f32_16x16x32_bf16 v[116:119], v[224:227], v[152:155], v[116:119]
	v_mfma_f32_16x16x32_bf16 v[104:107], v[216:219], v[160:163], v[104:107]
	v_mfma_f32_16x16x32_bf16 v[100:103], v[224:227], v[160:163], v[100:103]
	v_mfma_f32_16x16x32_bf16 v[88:91], v[216:219], v[200:203], v[88:91]
	v_mfma_f32_16x16x32_bf16 v[84:87], v[224:227], v[200:203], v[84:87]
	v_mfma_f32_16x16x32_bf16 v[72:75], v[216:219], v[208:211], v[72:75]
	v_mfma_f32_16x16x32_bf16 v[68:71], v[224:227], v[208:211], v[68:71]
	s_mov_b32 m0, s63
	v_lshl_add_u64 v[232:233], s[58:59], 0, v[174:175]
	s_barrier
	ds_read_b128 v[148:151], v199 offset:16384
	ds_read_b128 v[152:155], v199 offset:17408
	ds_read_b128 v[156:159], v199 offset:18432
	ds_read_b128 v[160:163], v199 offset:19456
	ds_read_b128 v[164:167], v199 offset:20480
	ds_read_b128 v[200:203], v199 offset:21504
	ds_read_b128 v[204:207], v199 offset:22528
	ds_read_b128 v[208:211], v199 offset:23552
	global_load_lds_dwordx4 v[232:233], off
	v_lshl_add_u64 v[234:235], s[58:59], 0, v[170:171]
	s_mov_b32 m0, s64
	s_nop 0
	global_load_lds_dwordx4 v[234:235], off
	s_barrier
	s_waitcnt lgkmcnt(0)
	v_mfma_f32_16x16x32_bf16 v[64:67], v[132:135], v[148:151], v[64:67]
	v_mfma_f32_16x16x32_bf16 v[60:63], v[140:143], v[148:151], v[60:63]
	v_mfma_f32_16x16x32_bf16 v[48:51], v[132:135], v[156:159], v[48:51]
	v_mfma_f32_16x16x32_bf16 v[44:47], v[140:143], v[156:159], v[44:47]
	v_mfma_f32_16x16x32_bf16 v[32:35], v[132:135], v[164:167], v[32:35]
	v_mfma_f32_16x16x32_bf16 v[28:31], v[140:143], v[164:167], v[28:31]
	v_mfma_f32_16x16x32_bf16 v[16:19], v[132:135], v[204:207], v[16:19]
	v_mfma_f32_16x16x32_bf16 v[12:15], v[140:143], v[204:207], v[12:15]
	v_mfma_f32_16x16x32_bf16 v[64:67], v[136:139], v[152:155], v[64:67]
	v_mfma_f32_16x16x32_bf16 v[60:63], v[144:147], v[152:155], v[60:63]
	v_mfma_f32_16x16x32_bf16 v[48:51], v[136:139], v[160:163], v[48:51]
	v_mfma_f32_16x16x32_bf16 v[44:47], v[144:147], v[160:163], v[44:47]
	v_mfma_f32_16x16x32_bf16 v[32:35], v[136:139], v[200:203], v[32:35]
	v_mfma_f32_16x16x32_bf16 v[28:31], v[144:147], v[200:203], v[28:31]
	v_mfma_f32_16x16x32_bf16 v[16:19], v[136:139], v[208:211], v[16:19]
	v_mfma_f32_16x16x32_bf16 v[12:15], v[144:147], v[208:211], v[12:15]
	s_barrier
	s_add_u32 vcc_lo, s56, 0x10000
	s_addc_u32 vcc_hi, s57, 0
	s_add_i32 s28, s93, s61
	v_lshl_add_u64 v[2:3], vcc, 0, v[172:173]
	s_mov_b32 m0, s28
	s_nop 0
	global_load_lds_dwordx4 v[2:3], off
	v_lshl_add_u64 v[2:3], vcc, 0, v[168:169]
	s_add_i32 m0, s28, 0x2000
	s_nop 0
	global_load_lds_dwordx4 v[2:3], off
	s_waitcnt vmcnt(6)
	s_barrier
	v_mfma_f32_16x16x32_bf16 v[56:59], v[212:215], v[148:151], v[56:59]
	v_mfma_f32_16x16x32_bf16 v[52:55], v[220:223], v[148:151], v[52:55]
	v_mfma_f32_16x16x32_bf16 v[40:43], v[212:215], v[156:159], v[40:43]
	v_mfma_f32_16x16x32_bf16 v[36:39], v[220:223], v[156:159], v[36:39]
	v_mfma_f32_16x16x32_bf16 v[24:27], v[212:215], v[164:167], v[24:27]
	v_mfma_f32_16x16x32_bf16 v[20:23], v[220:223], v[164:167], v[20:23]
	v_mfma_f32_16x16x32_bf16 v[8:11], v[212:215], v[204:207], v[8:11]
	v_mfma_f32_16x16x32_bf16 v[2:5], v[220:223], v[204:207], v[4:7]
	v_mfma_f32_16x16x32_bf16 v[56:59], v[216:219], v[152:155], v[56:59]
	v_mfma_f32_16x16x32_bf16 v[52:55], v[224:227], v[152:155], v[52:55]
	v_mfma_f32_16x16x32_bf16 v[40:43], v[216:219], v[160:163], v[40:43]
	v_mfma_f32_16x16x32_bf16 v[36:39], v[224:227], v[160:163], v[36:39]
	v_mfma_f32_16x16x32_bf16 v[24:27], v[216:219], v[200:203], v[24:27]
	v_mfma_f32_16x16x32_bf16 v[20:23], v[224:227], v[200:203], v[20:23]
	v_mfma_f32_16x16x32_bf16 v[8:11], v[216:219], v[208:211], v[8:11]
	v_mfma_f32_16x16x32_bf16 v[2:5], v[224:227], v[208:211], v[2:5]
	s_add_i32 s28, 0, 0x18000
	v_add_u32_e32 v1, s28, v196
	s_barrier
	ds_read_b128 v[132:135], v1
	ds_read_b128 v[136:139], v1 offset:1024
	ds_read_b128 v[140:143], v1 offset:2048
	ds_read_b128 v[144:147], v1 offset:3072
	s_add_u32 s58, s58, 0x40000
	s_addc_u32 s59, s59, 0
	s_mov_b32 m0, s65
	v_lshl_add_u64 v[6:7], s[58:59], 0, v[174:175]
	ds_read_b128 v[148:151], v199 offset:32768
	ds_read_b128 v[152:155], v199 offset:33792
	ds_read_b128 v[156:159], v199 offset:34816
	ds_read_b128 v[160:163], v199 offset:35840
	ds_read_b128 v[164:167], v199 offset:36864
	ds_read_b128 v[200:203], v199 offset:37888
	ds_read_b128 v[204:207], v199 offset:38912
	ds_read_b128 v[208:211], v199 offset:39936
	global_load_lds_dwordx4 v[6:7], off
	v_lshl_add_u64 v[6:7], s[58:59], 0, v[170:171]
	s_mov_b32 m0, s66
	s_nop 0
	global_load_lds_dwordx4 v[6:7], off
	s_waitcnt lgkmcnt(8)
	s_barrier
	s_waitcnt lgkmcnt(0)
	v_mfma_f32_16x16x32_bf16 v[128:131], v[132:135], v[148:151], v[128:131]
	v_mfma_f32_16x16x32_bf16 v[124:127], v[140:143], v[148:151], v[124:127]
	v_mfma_f32_16x16x32_bf16 v[112:115], v[132:135], v[156:159], v[112:115]
	v_mfma_f32_16x16x32_bf16 v[108:111], v[140:143], v[156:159], v[108:111]
	v_mfma_f32_16x16x32_bf16 v[96:99], v[132:135], v[164:167], v[96:99]
	v_mfma_f32_16x16x32_bf16 v[92:95], v[140:143], v[164:167], v[92:95]
	v_mfma_f32_16x16x32_bf16 v[80:83], v[132:135], v[204:207], v[80:83]
	v_mfma_f32_16x16x32_bf16 v[76:79], v[140:143], v[204:207], v[76:79]
	v_mfma_f32_16x16x32_bf16 v[128:131], v[136:139], v[152:155], v[128:131]
	v_mfma_f32_16x16x32_bf16 v[124:127], v[144:147], v[152:155], v[124:127]
	v_mfma_f32_16x16x32_bf16 v[112:115], v[136:139], v[160:163], v[112:115]
	v_mfma_f32_16x16x32_bf16 v[108:111], v[144:147], v[160:163], v[108:111]
	v_mfma_f32_16x16x32_bf16 v[96:99], v[136:139], v[200:203], v[96:99]
	v_mfma_f32_16x16x32_bf16 v[92:95], v[144:147], v[200:203], v[92:95]
	v_mfma_f32_16x16x32_bf16 v[80:83], v[136:139], v[208:211], v[80:83]
	v_mfma_f32_16x16x32_bf16 v[76:79], v[144:147], v[208:211], v[76:79]
	s_barrier
	s_add_i32 s29, 0, 0x1c000
	s_add_i32 s28, s28, s61
	v_add_u32_e32 v1, s29, v196
	v_lshl_add_u64 v[6:7], v[228:229], 0, s[0:1]
	s_mov_b32 m0, s28
	ds_read_b128 v[212:215], v1
	ds_read_b128 v[216:219], v1 offset:1024
	ds_read_b128 v[220:223], v1 offset:2048
	ds_read_b128 v[224:227], v1 offset:3072
	global_load_lds_dwordx4 v[6:7], off
	v_lshl_add_u64 v[6:7], v[230:231], 0, s[0:1]
	s_add_i32 m0, s28, 0x2000
	s_nop 0
	global_load_lds_dwordx4 v[6:7], off
	s_barrier
	s_waitcnt lgkmcnt(0)
	v_mfma_f32_16x16x32_bf16 v[120:123], v[212:215], v[148:151], v[120:123]
	v_mfma_f32_16x16x32_bf16 v[116:119], v[220:223], v[148:151], v[116:119]
	v_mfma_f32_16x16x32_bf16 v[104:107], v[212:215], v[156:159], v[104:107]
	v_mfma_f32_16x16x32_bf16 v[100:103], v[220:223], v[156:159], v[100:103]
	v_mfma_f32_16x16x32_bf16 v[88:91], v[212:215], v[164:167], v[88:91]
	v_mfma_f32_16x16x32_bf16 v[84:87], v[220:223], v[164:167], v[84:87]
	v_mfma_f32_16x16x32_bf16 v[72:75], v[212:215], v[204:207], v[72:75]
	v_mfma_f32_16x16x32_bf16 v[68:71], v[220:223], v[204:207], v[68:71]
	v_mfma_f32_16x16x32_bf16 v[120:123], v[216:219], v[152:155], v[120:123]
	v_mfma_f32_16x16x32_bf16 v[116:119], v[224:227], v[152:155], v[116:119]
	v_mfma_f32_16x16x32_bf16 v[104:107], v[216:219], v[160:163], v[104:107]
	v_mfma_f32_16x16x32_bf16 v[100:103], v[224:227], v[160:163], v[100:103]
	v_mfma_f32_16x16x32_bf16 v[88:91], v[216:219], v[200:203], v[88:91]
	v_mfma_f32_16x16x32_bf16 v[84:87], v[224:227], v[200:203], v[84:87]
	v_mfma_f32_16x16x32_bf16 v[72:75], v[216:219], v[208:211], v[72:75]
	v_mfma_f32_16x16x32_bf16 v[68:71], v[224:227], v[208:211], v[68:71]
	s_mov_b32 m0, s81
	v_lshl_add_u64 v[6:7], v[232:233], 0, s[0:1]
	s_barrier
	ds_read_b128 v[148:151], v199 offset:49152
	ds_read_b128 v[152:155], v199 offset:50176
	ds_read_b128 v[156:159], v199 offset:51200
	ds_read_b128 v[160:163], v199 offset:52224
	ds_read_b128 v[164:167], v199 offset:53248
	ds_read_b128 v[200:203], v199 offset:54272
	ds_read_b128 v[204:207], v199 offset:55296
	ds_read_b128 v[208:211], v199 offset:56320
	global_load_lds_dwordx4 v[6:7], off
	v_lshl_add_u64 v[6:7], v[234:235], 0, s[0:1]
	s_mov_b32 m0, s82
	s_nop 0
	global_load_lds_dwordx4 v[6:7], off
	s_barrier
	s_waitcnt lgkmcnt(0)
	v_mfma_f32_16x16x32_bf16 v[64:67], v[132:135], v[148:151], v[64:67]
	v_mfma_f32_16x16x32_bf16 v[60:63], v[140:143], v[148:151], v[60:63]
	v_mfma_f32_16x16x32_bf16 v[48:51], v[132:135], v[156:159], v[48:51]
	v_mfma_f32_16x16x32_bf16 v[44:47], v[140:143], v[156:159], v[44:47]
	v_mfma_f32_16x16x32_bf16 v[32:35], v[132:135], v[164:167], v[32:35]
	v_mfma_f32_16x16x32_bf16 v[28:31], v[140:143], v[164:167], v[28:31]
	v_mfma_f32_16x16x32_bf16 v[16:19], v[132:135], v[204:207], v[16:19]
	v_mfma_f32_16x16x32_bf16 v[12:15], v[140:143], v[204:207], v[12:15]
	v_mfma_f32_16x16x32_bf16 v[64:67], v[136:139], v[152:155], v[64:67]
	v_mfma_f32_16x16x32_bf16 v[60:63], v[144:147], v[152:155], v[60:63]
	v_mfma_f32_16x16x32_bf16 v[48:51], v[136:139], v[160:163], v[48:51]
	v_mfma_f32_16x16x32_bf16 v[44:47], v[144:147], v[160:163], v[44:47]
	v_mfma_f32_16x16x32_bf16 v[32:35], v[136:139], v[200:203], v[32:35]
	v_mfma_f32_16x16x32_bf16 v[28:31], v[144:147], v[200:203], v[28:31]
	v_mfma_f32_16x16x32_bf16 v[16:19], v[136:139], v[208:211], v[16:19]
	v_mfma_f32_16x16x32_bf16 v[12:15], v[144:147], v[208:211], v[12:15]
	s_barrier
	s_add_u32 s56, s56, 0x10080
	s_addc_u32 s57, s57, 0
	s_add_i32 s28, s29, s61
	v_lshl_add_u64 v[6:7], s[56:57], 0, v[172:173]
	s_mov_b32 m0, s28
	s_nop 0
	global_load_lds_dwordx4 v[6:7], off
	v_lshl_add_u64 v[6:7], s[56:57], 0, v[168:169]
	s_add_i32 m0, s28, 0x2000
	s_nop 0
	global_load_lds_dwordx4 v[6:7], off
	s_waitcnt vmcnt(6)
	s_barrier
	v_mfma_f32_16x16x32_bf16 v[56:59], v[212:215], v[148:151], v[56:59]
	v_mfma_f32_16x16x32_bf16 v[52:55], v[220:223], v[148:151], v[52:55]
	v_mfma_f32_16x16x32_bf16 v[40:43], v[212:215], v[156:159], v[40:43]
	v_mfma_f32_16x16x32_bf16 v[36:39], v[220:223], v[156:159], v[36:39]
	v_mfma_f32_16x16x32_bf16 v[24:27], v[212:215], v[164:167], v[24:27]
	v_mfma_f32_16x16x32_bf16 v[20:23], v[220:223], v[164:167], v[20:23]
	v_mfma_f32_16x16x32_bf16 v[6:9], v[212:215], v[204:207], v[8:11]
	v_mfma_f32_16x16x32_bf16 v[2:5], v[220:223], v[204:207], v[2:5]
	v_mfma_f32_16x16x32_bf16 v[56:59], v[216:219], v[152:155], v[56:59]
	v_mfma_f32_16x16x32_bf16 v[52:55], v[224:227], v[152:155], v[52:55]
	v_mfma_f32_16x16x32_bf16 v[40:43], v[216:219], v[160:163], v[40:43]
	v_mfma_f32_16x16x32_bf16 v[36:39], v[224:227], v[160:163], v[36:39]
	v_mfma_f32_16x16x32_bf16 v[24:27], v[216:219], v[200:203], v[24:27]
	v_mfma_f32_16x16x32_bf16 v[20:23], v[224:227], v[200:203], v[20:23]
	v_mfma_f32_16x16x32_bf16 v[8:11], v[216:219], v[208:211], v[6:9]
	v_mfma_f32_16x16x32_bf16 v[4:7], v[224:227], v[208:211], v[2:5]
	s_add_i32 s17, s17, 2
	s_add_u32 s54, s54, 0x100
	s_addc_u32 s55, s55, 0
	s_cmp_gt_u32 s17, 13
	s_barrier
	s_cbranch_scc1 .LBB0_659
	.p2align	6

.LBB0_739:
	s_ashr_i32 s57, s56, 31
	v_cmp_lt_i64_e32 vcc, s[58:59], v[208:209]
	s_lshl_b64 s[58:59], s[56:57], 19
	s_add_u32 s58, s68, s58
	s_addc_u32 s59, s69, s59
	s_and_b64 s[60:61], vcc, exec
	s_cselect_b32 s9, s59, s11
	s_cselect_b32 s13, s58, s10
	s_ashr_i32 s55, s54, 31
	s_lshl_b64 s[60:61], s[54:55], 19
	s_add_u32 s60, s76, s60
	s_addc_u32 s61, s77, s61
	s_and_b64 s[64:65], vcc, exec
	s_cselect_b32 s17, s61, s63
	s_cselect_b32 s44, s60, s62
	s_add_u32 s10, s10, 0x40080
	s_addc_u32 s11, s11, 0
	s_add_u32 s55, s62, 0x100
	v_mov_b32_e32 v0, 0
	s_addc_u32 s57, s63, 0
	s_mov_b32 s92, -2
	s_waitcnt lgkmcnt(0)
	v_mov_b64_e32 v[0:1], 0
	v_mov_b64_e32 v[2:3], 0
	v_mov_b64_e32 v[4:5], 0
	v_mov_b64_e32 v[6:7], 0
	v_mov_b64_e32 v[8:9], 0
	v_mov_b64_e32 v[10:11], 0
	v_mov_b64_e32 v[12:13], 0
	v_mov_b64_e32 v[14:15], 0
	v_mov_b64_e32 v[16:17], 0
	v_mov_b64_e32 v[18:19], 0
	v_mov_b64_e32 v[20:21], 0
	v_mov_b64_e32 v[22:23], 0
	v_mov_b64_e32 v[24:25], 0
	v_mov_b64_e32 v[26:27], 0
	v_mov_b64_e32 v[28:29], 0
	v_mov_b64_e32 v[30:31], 0
	v_mov_b64_e32 v[32:33], 0
	v_mov_b64_e32 v[34:35], 0
	v_mov_b64_e32 v[36:37], 0
	v_mov_b64_e32 v[38:39], 0
	v_mov_b64_e32 v[40:41], 0
	v_mov_b64_e32 v[42:43], 0
	v_mov_b64_e32 v[44:45], 0
	v_mov_b64_e32 v[46:47], 0
	v_mov_b64_e32 v[48:49], 0
	v_mov_b64_e32 v[50:51], 0
	v_mov_b64_e32 v[52:53], 0
	v_mov_b64_e32 v[54:55], 0
	v_mov_b64_e32 v[56:57], 0
	v_mov_b64_e32 v[58:59], 0
	v_mov_b64_e32 v[60:61], 0
	v_mov_b64_e32 v[62:63], 0
	v_mov_b64_e32 v[72:73], 0
	v_mov_b64_e32 v[74:75], 0
	v_mov_b64_e32 v[76:77], 0
	v_mov_b64_e32 v[78:79], 0
	v_mov_b64_e32 v[80:81], 0
	v_mov_b64_e32 v[82:83], 0
	v_mov_b64_e32 v[88:89], 0
	v_mov_b64_e32 v[90:91], 0
	v_mov_b64_e32 v[96:97], 0
	v_mov_b64_e32 v[98:99], 0
	v_mov_b64_e32 v[100:101], 0
	v_mov_b64_e32 v[102:103], 0
	v_mov_b64_e32 v[104:105], 0
	v_mov_b64_e32 v[106:107], 0
	v_mov_b64_e32 v[108:109], 0
	v_mov_b64_e32 v[110:111], 0
	v_mov_b64_e32 v[112:113], 0
	v_mov_b64_e32 v[114:115], 0
	v_mov_b64_e32 v[116:117], 0
	v_mov_b64_e32 v[118:119], 0
	v_mov_b64_e32 v[120:121], 0
	v_mov_b64_e32 v[122:123], 0
	v_mov_b64_e32 v[124:125], 0
	v_mov_b64_e32 v[126:127], 0
	v_mov_b64_e32 v[128:129], 0
	v_mov_b64_e32 v[130:131], 0
	v_mov_b64_e32 v[132:133], 0
	v_mov_b64_e32 v[134:135], 0
	v_mov_b64_e32 v[136:137], 0
	v_mov_b64_e32 v[138:139], 0
	v_mov_b64_e32 v[140:141], 0
	v_mov_b64_e32 v[142:143], 0
	.p2align	6

.LBB0_903:
	s_ashr_i32 s45, s44, 31
	v_cmp_lt_i64_e32 vcc, s[0:1], v[142:143]
	s_lshl_b64 s[0:1], s[44:45], 19
	s_add_u32 s46, s42, s0
	s_addc_u32 s47, s43, s1
	s_and_b64 s[0:1], vcc, exec
	s_cselect_b32 s7, s47, s53
	s_cselect_b32 s45, s46, s52
	s_ashr_i32 s37, s36, 31
	s_lshl_b64 s[0:1], s[36:37], 19
	s_add_u32 s48, s74, s0
	s_addc_u32 s49, s75, s1
	s_and_b64 s[0:1], vcc, exec
	s_cselect_b32 s37, s49, s51
	s_cselect_b32 s67, s48, s50
	s_add_u32 s0, s52, 0x40080
	s_addc_u32 s1, s53, 0
	s_add_u32 s76, s50, 0x100
	v_mov_b32_e32 v0, 0
	s_addc_u32 s77, s51, 0
	s_mov_b32 s78, -2
	v_mov_b64_e32 v[0:1], 0
	v_mov_b64_e32 v[2:3], 0
	v_mov_b64_e32 v[4:5], 0
	v_mov_b64_e32 v[6:7], 0
	v_mov_b64_e32 v[8:9], 0
	v_mov_b64_e32 v[10:11], 0
	v_mov_b64_e32 v[12:13], 0
	v_mov_b64_e32 v[14:15], 0
	v_mov_b64_e32 v[16:17], 0
	v_mov_b64_e32 v[18:19], 0
	v_mov_b64_e32 v[20:21], 0
	v_mov_b64_e32 v[22:23], 0
	v_mov_b64_e32 v[24:25], 0
	v_mov_b64_e32 v[26:27], 0
	v_mov_b64_e32 v[28:29], 0
	v_mov_b64_e32 v[30:31], 0
	v_mov_b64_e32 v[32:33], 0
	v_mov_b64_e32 v[34:35], 0
	v_mov_b64_e32 v[36:37], 0
	v_mov_b64_e32 v[38:39], 0
	v_mov_b64_e32 v[40:41], 0
	v_mov_b64_e32 v[42:43], 0
	v_mov_b64_e32 v[44:45], 0
	v_mov_b64_e32 v[46:47], 0
	v_mov_b64_e32 v[48:49], 0
	v_mov_b64_e32 v[50:51], 0
	v_mov_b64_e32 v[52:53], 0
	v_mov_b64_e32 v[54:55], 0
	v_mov_b64_e32 v[56:57], 0
	v_mov_b64_e32 v[58:59], 0
	v_mov_b64_e32 v[60:61], 0
	v_mov_b64_e32 v[62:63], 0
	v_mov_b64_e32 v[64:65], 0
	v_mov_b64_e32 v[66:67], 0
	v_mov_b64_e32 v[68:69], 0
	v_mov_b64_e32 v[70:71], 0
	v_mov_b64_e32 v[72:73], 0
	v_mov_b64_e32 v[74:75], 0
	v_mov_b64_e32 v[76:77], 0
	v_mov_b64_e32 v[78:79], 0
	v_mov_b64_e32 v[80:81], 0
	v_mov_b64_e32 v[82:83], 0
	v_mov_b64_e32 v[84:85], 0
	v_mov_b64_e32 v[86:87], 0
	v_mov_b64_e32 v[88:89], 0
	v_mov_b64_e32 v[90:91], 0
	v_mov_b64_e32 v[92:93], 0
	v_mov_b64_e32 v[94:95], 0
	v_mov_b64_e32 v[96:97], 0
	v_mov_b64_e32 v[98:99], 0
	v_mov_b64_e32 v[100:101], 0
	v_mov_b64_e32 v[102:103], 0
	v_mov_b64_e32 v[104:105], 0
	v_mov_b64_e32 v[106:107], 0
	v_mov_b64_e32 v[108:109], 0
	v_mov_b64_e32 v[110:111], 0
	v_mov_b64_e32 v[112:113], 0
	v_mov_b64_e32 v[114:115], 0
	v_mov_b64_e32 v[116:117], 0
	v_mov_b64_e32 v[118:119], 0
	v_mov_b64_e32 v[120:121], 0
	v_mov_b64_e32 v[122:123], 0
	v_mov_b64_e32 v[124:125], 0
	v_mov_b64_e32 v[126:127], 0
	.p2align	6

.LBB0_996:
	s_ashr_i32 s41, s40, 31
	v_cmp_lt_i64_e32 vcc, s[44:45], v[148:149]
	s_lshl_b64 s[44:45], s[40:41], 18
	s_add_u32 s44, s74, s44
	s_addc_u32 s45, s75, s45
	s_and_b64 s[46:47], vcc, exec
	s_cselect_b32 s9, s45, s49
	s_cselect_b32 s41, s44, s48
	s_ashr_i32 s39, s38, 31
	s_lshl_b64 s[46:47], s[38:39], 18
	s_add_u32 s46, s72, s46
	s_addc_u32 s47, s73, s47
	s_and_b64 s[52:53], vcc, exec
	s_cselect_b32 s39, s47, s51
	s_cselect_b32 s76, s46, s50
	s_add_u32 s48, s48, 0x20080
	s_addc_u32 s49, s49, 0
	s_add_u32 s77, s50, 0x100
	v_mov_b32_e32 v0, 0
	s_addc_u32 s78, s51, 0
	s_mov_b32 s79, -2
	s_waitcnt lgkmcnt(0)
	v_mov_b64_e32 v[0:1], 0
	v_mov_b64_e32 v[2:3], 0
	v_mov_b64_e32 v[4:5], 0
	v_mov_b64_e32 v[6:7], 0
	v_mov_b64_e32 v[8:9], 0
	v_mov_b64_e32 v[10:11], 0
	v_mov_b64_e32 v[12:13], 0
	v_mov_b64_e32 v[14:15], 0
	v_mov_b64_e32 v[16:17], 0
	v_mov_b64_e32 v[18:19], 0
	v_mov_b64_e32 v[20:21], 0
	v_mov_b64_e32 v[22:23], 0
	v_mov_b64_e32 v[24:25], 0
	v_mov_b64_e32 v[26:27], 0
	v_mov_b64_e32 v[28:29], 0
	v_mov_b64_e32 v[30:31], 0
	v_mov_b64_e32 v[32:33], 0
	v_mov_b64_e32 v[34:35], 0
	v_mov_b64_e32 v[36:37], 0
	v_mov_b64_e32 v[38:39], 0
	v_mov_b64_e32 v[40:41], 0
	v_mov_b64_e32 v[42:43], 0
	v_mov_b64_e32 v[44:45], 0
	v_mov_b64_e32 v[46:47], 0
	v_mov_b64_e32 v[48:49], 0
	v_mov_b64_e32 v[50:51], 0
	v_mov_b64_e32 v[52:53], 0
	v_mov_b64_e32 v[54:55], 0
	v_mov_b64_e32 v[56:57], 0
	v_mov_b64_e32 v[58:59], 0
	v_mov_b64_e32 v[60:61], 0
	v_mov_b64_e32 v[62:63], 0
	v_mov_b64_e32 v[64:65], 0
	v_mov_b64_e32 v[66:67], 0
	v_mov_b64_e32 v[68:69], 0
	v_mov_b64_e32 v[70:71], 0
	v_mov_b64_e32 v[72:73], 0
	v_mov_b64_e32 v[74:75], 0
	v_mov_b64_e32 v[76:77], 0
	v_mov_b64_e32 v[78:79], 0
	v_mov_b64_e32 v[80:81], 0
	v_mov_b64_e32 v[82:83], 0
	v_mov_b64_e32 v[84:85], 0
	v_mov_b64_e32 v[86:87], 0
	v_mov_b64_e32 v[88:89], 0
	v_mov_b64_e32 v[90:91], 0
	v_mov_b64_e32 v[92:93], 0
	v_mov_b64_e32 v[94:95], 0
	v_mov_b64_e32 v[96:97], 0
	v_mov_b64_e32 v[98:99], 0
	v_mov_b64_e32 v[100:101], 0
	v_mov_b64_e32 v[102:103], 0
	v_mov_b64_e32 v[104:105], 0
	v_mov_b64_e32 v[106:107], 0
	v_mov_b64_e32 v[108:109], 0
	v_mov_b64_e32 v[110:111], 0
	v_mov_b64_e32 v[112:113], 0
	v_mov_b64_e32 v[114:115], 0
	v_mov_b64_e32 v[116:117], 0
	v_mov_b64_e32 v[118:119], 0
	v_mov_b64_e32 v[120:121], 0
	v_mov_b64_e32 v[122:123], 0
	v_mov_b64_e32 v[124:125], 0
	v_mov_b64_e32 v[126:127], 0
	.p2align	6

.LBB0_1092:
	s_ashr_i32 s37, s36, 31
	v_cmp_lt_i64_e32 vcc, s[0:1], v[142:143]
	s_lshl_b64 s[0:1], s[36:37], 19
	s_add_u32 s38, s68, s0
	s_addc_u32 s39, s69, s1
	s_and_b64 s[0:1], vcc, exec
	s_cselect_b32 s37, s39, s45
	s_cselect_b32 s60, s38, s44
	s_ashr_i32 s13, s12, 31
	s_lshl_b64 s[0:1], s[12:13], 19
	s_add_u32 s40, s70, s0
	s_addc_u32 s41, s71, s1
	s_and_b64 s[0:1], vcc, exec
	s_cselect_b32 s13, s41, s43
	s_cselect_b32 s61, s40, s42
	s_add_u32 s0, s44, 0x40080
	s_addc_u32 s1, s45, 0
	s_add_u32 s62, s42, 0x100
	s_addc_u32 s63, s43, 0
	s_mov_b32 s64, -2
	ds_read_b128 v[146:149], v167
	ds_read_b128 v[150:153], v167 offset:1024
	ds_read_b128 v[178:181], v167 offset:2048
	ds_read_b128 v[182:185], v167 offset:3072
	s_add_u32 s28, s0, 0xfffc0080
	s_addc_u32 s29, s1, -1
	s_cmp_eq_u32 s64, 12
	s_cselect_b32 s45, s37, s29
	s_cselect_b32 s44, s60, s28
	s_cselect_b32 s43, s13, s63
	s_cselect_b32 s42, s61, s62
	v_lshl_add_u64 v[156:157], s[0:1], 0, v[138:139]
	s_add_i32 m0, s47, 0xc000
	ds_read_b128 v[186:189], v171
	ds_read_b128 v[196:199], v171 offset:1024
	ds_read_b128 v[200:203], v171 offset:2048
	ds_read_b128 v[204:207], v171 offset:3072
	ds_read_b128 v[208:211], v171 offset:4096
	ds_read_b128 v[212:215], v171 offset:5120
	ds_read_b128 v[216:219], v171 offset:6144
	ds_read_b128 v[220:223], v171 offset:7168
	global_load_lds_dwordx4 v[156:157], off
	v_lshl_add_u64 v[156:157], s[0:1], 0, v[140:141]
	s_add_i32 m0, s47, 0xe000
	s_nop 0
	global_load_lds_dwordx4 v[156:157], off
	s_waitcnt lgkmcnt(8)
	s_barrier
	s_waitcnt lgkmcnt(0)
	v_mfma_f32_16x16x32_bf16 v[124:127], v[146:149], v[186:189], 0
	v_mfma_f32_16x16x32_bf16 v[120:123], v[178:181], v[186:189], 0
	v_mfma_f32_16x16x32_bf16 v[108:111], v[146:149], v[200:203], 0
	v_mfma_f32_16x16x32_bf16 v[104:107], v[178:181], v[200:203], 0
	v_mfma_f32_16x16x32_bf16 v[92:95], v[146:149], v[208:211], 0
	v_mfma_f32_16x16x32_bf16 v[88:91], v[178:181], v[208:211], 0
	v_mfma_f32_16x16x32_bf16 v[76:79], v[146:149], v[216:219], 0
	v_mfma_f32_16x16x32_bf16 v[72:75], v[178:181], v[216:219], 0
	v_mfma_f32_16x16x32_bf16 v[124:127], v[150:153], v[196:199], v[124:127]
	v_mfma_f32_16x16x32_bf16 v[120:123], v[182:185], v[196:199], v[120:123]
	v_mfma_f32_16x16x32_bf16 v[108:111], v[150:153], v[204:207], v[108:111]
	v_mfma_f32_16x16x32_bf16 v[104:107], v[182:185], v[204:207], v[104:107]
	v_mfma_f32_16x16x32_bf16 v[92:95], v[150:153], v[212:215], v[92:95]
	v_mfma_f32_16x16x32_bf16 v[88:91], v[182:185], v[212:215], v[88:91]
	v_mfma_f32_16x16x32_bf16 v[76:79], v[150:153], v[220:223], v[76:79]
	v_mfma_f32_16x16x32_bf16 v[72:75], v[182:185], v[220:223], v[72:75]
	s_barrier
	s_add_i32 s28, s56, s11
	v_lshl_add_u64 v[156:157], s[42:43], 0, v[132:133]
	s_mov_b32 m0, s28
	ds_read_b128 v[224:227], v175
	ds_read_b128 v[228:231], v175 offset:1024
	ds_read_b128 v[232:235], v175 offset:2048
	ds_read_b128 v[236:239], v175 offset:3072
	global_load_lds_dwordx4 v[156:157], off
	v_lshl_add_u64 v[160:161], s[42:43], 0, v[128:129]
	s_add_i32 m0, s28, 0x2000
	s_nop 0
	global_load_lds_dwordx4 v[160:161], off
	s_barrier
	s_waitcnt lgkmcnt(0)
	v_mfma_f32_16x16x32_bf16 v[116:119], v[224:227], v[186:189], 0
	v_mfma_f32_16x16x32_bf16 v[112:115], v[232:235], v[186:189], 0
	v_mfma_f32_16x16x32_bf16 v[100:103], v[224:227], v[200:203], 0
	v_mfma_f32_16x16x32_bf16 v[96:99], v[232:235], v[200:203], 0
	v_mfma_f32_16x16x32_bf16 v[84:87], v[224:227], v[208:211], 0
	v_mfma_f32_16x16x32_bf16 v[80:83], v[232:235], v[208:211], 0
	v_mfma_f32_16x16x32_bf16 v[68:71], v[224:227], v[216:219], 0
	v_mfma_f32_16x16x32_bf16 v[64:67], v[232:235], v[216:219], 0
	v_mfma_f32_16x16x32_bf16 v[116:119], v[228:231], v[196:199], v[116:119]
	v_mfma_f32_16x16x32_bf16 v[112:115], v[236:239], v[196:199], v[112:115]
	v_mfma_f32_16x16x32_bf16 v[100:103], v[228:231], v[204:207], v[100:103]
	v_mfma_f32_16x16x32_bf16 v[96:99], v[236:239], v[204:207], v[96:99]
	v_mfma_f32_16x16x32_bf16 v[84:87], v[228:231], v[212:215], v[84:87]
	v_mfma_f32_16x16x32_bf16 v[80:83], v[236:239], v[212:215], v[80:83]
	v_mfma_f32_16x16x32_bf16 v[68:71], v[228:231], v[220:223], v[68:71]
	v_mfma_f32_16x16x32_bf16 v[64:67], v[236:239], v[220:223], v[64:67]
	s_mov_b32 m0, s47
	v_lshl_add_u64 v[164:165], s[44:45], 0, v[134:135]
	s_barrier
	ds_read_b128 v[186:189], v171 offset:16384
	ds_read_b128 v[196:199], v171 offset:17408
	ds_read_b128 v[200:203], v171 offset:18432
	ds_read_b128 v[204:207], v171 offset:19456
	ds_read_b128 v[208:211], v171 offset:20480
	ds_read_b128 v[212:215], v171 offset:21504
	ds_read_b128 v[216:219], v171 offset:22528
	ds_read_b128 v[220:223], v171 offset:23552
	global_load_lds_dwordx4 v[164:165], off
	v_lshl_add_u64 v[168:169], s[44:45], 0, v[130:131]
	s_mov_b32 m0, s48
	s_nop 0
	global_load_lds_dwordx4 v[168:169], off
	s_barrier
	s_waitcnt lgkmcnt(0)
	v_mfma_f32_16x16x32_bf16 v[60:63], v[146:149], v[186:189], 0
	v_mfma_f32_16x16x32_bf16 v[56:59], v[178:181], v[186:189], 0
	v_mfma_f32_16x16x32_bf16 v[44:47], v[146:149], v[200:203], 0
	v_mfma_f32_16x16x32_bf16 v[40:43], v[178:181], v[200:203], 0
	v_mfma_f32_16x16x32_bf16 v[28:31], v[146:149], v[208:211], 0
	v_mfma_f32_16x16x32_bf16 v[24:27], v[178:181], v[208:211], 0
	v_mfma_f32_16x16x32_bf16 v[12:15], v[146:149], v[216:219], 0
	v_mfma_f32_16x16x32_bf16 v[8:11], v[178:181], v[216:219], 0
	v_mfma_f32_16x16x32_bf16 v[60:63], v[150:153], v[196:199], v[60:63]
	v_mfma_f32_16x16x32_bf16 v[56:59], v[182:185], v[196:199], v[56:59]
	v_mfma_f32_16x16x32_bf16 v[44:47], v[150:153], v[204:207], v[44:47]
	v_mfma_f32_16x16x32_bf16 v[40:43], v[182:185], v[204:207], v[40:43]
	v_mfma_f32_16x16x32_bf16 v[28:31], v[150:153], v[212:215], v[28:31]
	v_mfma_f32_16x16x32_bf16 v[24:27], v[182:185], v[212:215], v[24:27]
	v_mfma_f32_16x16x32_bf16 v[12:15], v[150:153], v[220:223], v[12:15]
	v_mfma_f32_16x16x32_bf16 v[8:11], v[182:185], v[220:223], v[8:11]
	s_barrier
	s_add_u32 s66, s42, 0x40000
	s_addc_u32 s67, s43, 0
	s_add_i32 s28, s57, s11
	v_lshl_add_u64 v[146:147], s[66:67], 0, v[132:133]
	s_mov_b32 m0, s28
	s_nop 0
	global_load_lds_dwordx4 v[146:147], off
	v_lshl_add_u64 v[146:147], s[66:67], 0, v[128:129]
	s_add_i32 m0, s28, 0x2000
	s_nop 0
	global_load_lds_dwordx4 v[146:147], off
	s_waitcnt vmcnt(6)
	s_barrier
	v_mfma_f32_16x16x32_bf16 v[52:55], v[224:227], v[186:189], 0
	v_mfma_f32_16x16x32_bf16 v[48:51], v[232:235], v[186:189], 0
	v_mfma_f32_16x16x32_bf16 v[36:39], v[224:227], v[200:203], 0
	v_mfma_f32_16x16x32_bf16 v[32:35], v[232:235], v[200:203], 0
	v_mfma_f32_16x16x32_bf16 v[20:23], v[224:227], v[208:211], 0
	v_mfma_f32_16x16x32_bf16 v[16:19], v[232:235], v[208:211], 0
	v_mfma_f32_16x16x32_bf16 v[4:7], v[224:227], v[216:219], 0
	v_mfma_f32_16x16x32_bf16 v[0:3], v[232:235], v[216:219], 0
	v_mfma_f32_16x16x32_bf16 v[52:55], v[228:231], v[196:199], v[52:55]
	v_mfma_f32_16x16x32_bf16 v[48:51], v[236:239], v[196:199], v[48:51]
	v_mfma_f32_16x16x32_bf16 v[36:39], v[228:231], v[204:207], v[36:39]
	v_mfma_f32_16x16x32_bf16 v[32:35], v[236:239], v[204:207], v[32:35]
	v_mfma_f32_16x16x32_bf16 v[20:23], v[228:231], v[212:215], v[20:23]
	v_mfma_f32_16x16x32_bf16 v[16:19], v[236:239], v[212:215], v[16:19]
	v_mfma_f32_16x16x32_bf16 v[4:7], v[228:231], v[220:223], v[4:7]
	v_mfma_f32_16x16x32_bf16 v[0:3], v[236:239], v[220:223], v[0:3]
	s_add_i32 s28, 0, 0x18000
	v_add_u32_e32 v154, s28, v159
	s_barrier
	ds_read_b128 v[146:149], v154
	ds_read_b128 v[150:153], v154 offset:1024
	ds_read_b128 v[178:181], v154 offset:2048
	ds_read_b128 v[182:185], v154 offset:3072
	s_add_u32 s44, s44, 0x40000
	s_addc_u32 s45, s45, 0
	s_mov_b32 m0, s49
	v_lshl_add_u64 v[172:173], s[44:45], 0, v[134:135]
	ds_read_b128 v[186:189], v171 offset:32768
	ds_read_b128 v[196:199], v171 offset:33792
	ds_read_b128 v[200:203], v171 offset:34816
	ds_read_b128 v[204:207], v171 offset:35840
	ds_read_b128 v[208:211], v171 offset:36864
	ds_read_b128 v[212:215], v171 offset:37888
	ds_read_b128 v[216:219], v171 offset:38912
	ds_read_b128 v[220:223], v171 offset:39936
	global_load_lds_dwordx4 v[172:173], off
	v_lshl_add_u64 v[172:173], s[44:45], 0, v[130:131]
	s_mov_b32 m0, s50
	s_nop 0
	global_load_lds_dwordx4 v[172:173], off
	s_waitcnt lgkmcnt(8)
	s_barrier
	s_waitcnt lgkmcnt(0)
	v_mfma_f32_16x16x32_bf16 v[124:127], v[146:149], v[186:189], v[124:127]
	v_mfma_f32_16x16x32_bf16 v[120:123], v[178:181], v[186:189], v[120:123]
	v_mfma_f32_16x16x32_bf16 v[108:111], v[146:149], v[200:203], v[108:111]
	v_mfma_f32_16x16x32_bf16 v[104:107], v[178:181], v[200:203], v[104:107]
	v_mfma_f32_16x16x32_bf16 v[92:95], v[146:149], v[208:211], v[92:95]
	v_mfma_f32_16x16x32_bf16 v[88:91], v[178:181], v[208:211], v[88:91]
	v_mfma_f32_16x16x32_bf16 v[76:79], v[146:149], v[216:219], v[76:79]
	v_mfma_f32_16x16x32_bf16 v[72:75], v[178:181], v[216:219], v[72:75]
	v_mfma_f32_16x16x32_bf16 v[124:127], v[150:153], v[196:199], v[124:127]
	v_mfma_f32_16x16x32_bf16 v[120:123], v[182:185], v[196:199], v[120:123]
	v_mfma_f32_16x16x32_bf16 v[108:111], v[150:153], v[204:207], v[108:111]
	v_mfma_f32_16x16x32_bf16 v[104:107], v[182:185], v[204:207], v[104:107]
	v_mfma_f32_16x16x32_bf16 v[92:95], v[150:153], v[212:215], v[92:95]
	v_mfma_f32_16x16x32_bf16 v[88:91], v[182:185], v[212:215], v[88:91]
	v_mfma_f32_16x16x32_bf16 v[76:79], v[150:153], v[220:223], v[76:79]
	v_mfma_f32_16x16x32_bf16 v[72:75], v[182:185], v[220:223], v[72:75]
	s_barrier
	s_add_i32 s29, 0, 0x1c000
	s_add_i32 s28, s28, s11
	v_add_u32_e32 v154, s29, v159
	v_lshl_add_u64 v[156:157], v[156:157], 0, s[6:7]
	s_mov_b32 m0, s28
	ds_read_b128 v[224:227], v154
	ds_read_b128 v[228:231], v154 offset:1024
	ds_read_b128 v[232:235], v154 offset:2048
	ds_read_b128 v[236:239], v154 offset:3072
	global_load_lds_dwordx4 v[156:157], off
	v_lshl_add_u64 v[156:157], v[160:161], 0, s[6:7]
	s_add_i32 m0, s28, 0x2000
	s_nop 0
	global_load_lds_dwordx4 v[156:157], off
	s_barrier
	s_waitcnt lgkmcnt(0)
	v_mfma_f32_16x16x32_bf16 v[116:119], v[224:227], v[186:189], v[116:119]
	v_mfma_f32_16x16x32_bf16 v[112:115], v[232:235], v[186:189], v[112:115]
	v_mfma_f32_16x16x32_bf16 v[100:103], v[224:227], v[200:203], v[100:103]
	v_mfma_f32_16x16x32_bf16 v[96:99], v[232:235], v[200:203], v[96:99]
	v_mfma_f32_16x16x32_bf16 v[84:87], v[224:227], v[208:211], v[84:87]
	v_mfma_f32_16x16x32_bf16 v[80:83], v[232:235], v[208:211], v[80:83]
	v_mfma_f32_16x16x32_bf16 v[68:71], v[224:227], v[216:219], v[68:71]
	v_mfma_f32_16x16x32_bf16 v[64:67], v[232:235], v[216:219], v[64:67]
	v_mfma_f32_16x16x32_bf16 v[116:119], v[228:231], v[196:199], v[116:119]
	v_mfma_f32_16x16x32_bf16 v[112:115], v[236:239], v[196:199], v[112:115]
	v_mfma_f32_16x16x32_bf16 v[100:103], v[228:231], v[204:207], v[100:103]
	v_mfma_f32_16x16x32_bf16 v[96:99], v[236:239], v[204:207], v[96:99]
	v_mfma_f32_16x16x32_bf16 v[84:87], v[228:231], v[212:215], v[84:87]
	v_mfma_f32_16x16x32_bf16 v[80:83], v[236:239], v[212:215], v[80:83]
	v_mfma_f32_16x16x32_bf16 v[68:71], v[228:231], v[220:223], v[68:71]
	v_mfma_f32_16x16x32_bf16 v[64:67], v[236:239], v[220:223], v[64:67]
	s_mov_b32 m0, s53
	v_lshl_add_u64 v[156:157], v[164:165], 0, s[6:7]
	s_barrier
	ds_read_b128 v[186:189], v171 offset:49152
	ds_read_b128 v[196:199], v171 offset:50176
	ds_read_b128 v[200:203], v171 offset:51200
	ds_read_b128 v[204:207], v171 offset:52224
	ds_read_b128 v[208:211], v171 offset:53248
	ds_read_b128 v[212:215], v171 offset:54272
	ds_read_b128 v[216:219], v171 offset:55296
	ds_read_b128 v[220:223], v171 offset:56320
	global_load_lds_dwordx4 v[156:157], off
	v_lshl_add_u64 v[156:157], v[168:169], 0, s[6:7]
	s_mov_b32 m0, s54
	s_nop 0
	global_load_lds_dwordx4 v[156:157], off
	s_barrier
	s_waitcnt lgkmcnt(0)
	v_mfma_f32_16x16x32_bf16 v[60:63], v[146:149], v[186:189], v[60:63]
	v_mfma_f32_16x16x32_bf16 v[56:59], v[178:181], v[186:189], v[56:59]
	v_mfma_f32_16x16x32_bf16 v[44:47], v[146:149], v[200:203], v[44:47]
	v_mfma_f32_16x16x32_bf16 v[40:43], v[178:181], v[200:203], v[40:43]
	v_mfma_f32_16x16x32_bf16 v[28:31], v[146:149], v[208:211], v[28:31]
	v_mfma_f32_16x16x32_bf16 v[24:27], v[178:181], v[208:211], v[24:27]
	v_mfma_f32_16x16x32_bf16 v[12:15], v[146:149], v[216:219], v[12:15]
	v_mfma_f32_16x16x32_bf16 v[8:11], v[178:181], v[216:219], v[8:11]
	v_mfma_f32_16x16x32_bf16 v[60:63], v[150:153], v[196:199], v[60:63]
	v_mfma_f32_16x16x32_bf16 v[56:59], v[182:185], v[196:199], v[56:59]
	v_mfma_f32_16x16x32_bf16 v[44:47], v[150:153], v[204:207], v[44:47]
	v_mfma_f32_16x16x32_bf16 v[40:43], v[182:185], v[204:207], v[40:43]
	v_mfma_f32_16x16x32_bf16 v[28:31], v[150:153], v[212:215], v[28:31]
	v_mfma_f32_16x16x32_bf16 v[24:27], v[182:185], v[212:215], v[24:27]
	v_mfma_f32_16x16x32_bf16 v[12:15], v[150:153], v[220:223], v[12:15]
	v_mfma_f32_16x16x32_bf16 v[8:11], v[182:185], v[220:223], v[8:11]
	s_barrier
	s_add_u32 s42, s42, 0x40080
	s_addc_u32 s43, s43, 0
	s_add_i32 s28, s29, s11
	v_lshl_add_u64 v[146:147], s[42:43], 0, v[132:133]
	s_mov_b32 m0, s28
	s_nop 0
	global_load_lds_dwordx4 v[146:147], off
	v_lshl_add_u64 v[146:147], s[42:43], 0, v[128:129]
	s_add_i32 m0, s28, 0x2000
	s_nop 0
	global_load_lds_dwordx4 v[146:147], off
	s_waitcnt vmcnt(6)
	s_barrier
	v_mfma_f32_16x16x32_bf16 v[52:55], v[224:227], v[186:189], v[52:55]
	v_mfma_f32_16x16x32_bf16 v[48:51], v[232:235], v[186:189], v[48:51]
	v_mfma_f32_16x16x32_bf16 v[36:39], v[224:227], v[200:203], v[36:39]
	v_mfma_f32_16x16x32_bf16 v[32:35], v[232:235], v[200:203], v[32:35]
	v_mfma_f32_16x16x32_bf16 v[20:23], v[224:227], v[208:211], v[20:23]
	v_mfma_f32_16x16x32_bf16 v[16:19], v[232:235], v[208:211], v[16:19]
	v_mfma_f32_16x16x32_bf16 v[4:7], v[224:227], v[216:219], v[4:7]
	v_mfma_f32_16x16x32_bf16 v[0:3], v[232:235], v[216:219], v[0:3]
	v_mfma_f32_16x16x32_bf16 v[52:55], v[228:231], v[196:199], v[52:55]
	v_mfma_f32_16x16x32_bf16 v[48:51], v[236:239], v[196:199], v[48:51]
	v_mfma_f32_16x16x32_bf16 v[36:39], v[228:231], v[204:207], v[36:39]
	v_mfma_f32_16x16x32_bf16 v[32:35], v[236:239], v[204:207], v[32:35]
	v_mfma_f32_16x16x32_bf16 v[20:23], v[228:231], v[212:215], v[20:23]
	v_mfma_f32_16x16x32_bf16 v[16:19], v[236:239], v[212:215], v[16:19]
	v_mfma_f32_16x16x32_bf16 v[4:7], v[228:231], v[220:223], v[4:7]
	v_mfma_f32_16x16x32_bf16 v[0:3], v[236:239], v[220:223], v[0:3]
	s_add_i32 s64, s64, 2
	s_add_u32 s0, s0, 0x100
	s_addc_u32 s1, s1, 0
	s_add_u32 s62, s62, 0x100
	s_addc_u32 s63, s63, 0
	s_cmp_gt_u32 s64, 13
	s_barrier
	s_cbranch_scc0 .LBB0_1093
	.p2align	6

.LBB0_1168:
	s_add_u32 s63, s42, 0x100
	v_mov_b32_e32 v0, 0
	s_addc_u32 s64, s43, 0
	s_mov_b32 s65, -2
	s_waitcnt lgkmcnt(0)
	v_mov_b64_e32 v[0:1], 0
	v_mov_b64_e32 v[2:3], 0
	v_mov_b64_e32 v[4:5], 0
	v_mov_b64_e32 v[6:7], 0
	v_mov_b64_e32 v[8:9], 0
	v_mov_b64_e32 v[10:11], 0
	v_mov_b64_e32 v[12:13], 0
	v_mov_b64_e32 v[14:15], 0
	v_mov_b64_e32 v[16:17], 0
	v_mov_b64_e32 v[18:19], 0
	v_mov_b64_e32 v[20:21], 0
	v_mov_b64_e32 v[22:23], 0
	v_mov_b64_e32 v[24:25], 0
	v_mov_b64_e32 v[26:27], 0
	v_mov_b64_e32 v[28:29], 0
	v_mov_b64_e32 v[30:31], 0
	v_mov_b64_e32 v[32:33], 0
	v_mov_b64_e32 v[34:35], 0
	v_mov_b64_e32 v[36:37], 0
	v_mov_b64_e32 v[38:39], 0
	v_mov_b64_e32 v[40:41], 0
	v_mov_b64_e32 v[42:43], 0
	v_mov_b64_e32 v[44:45], 0
	v_mov_b64_e32 v[46:47], 0
	v_mov_b64_e32 v[48:49], 0
	v_mov_b64_e32 v[50:51], 0
	v_mov_b64_e32 v[52:53], 0
	v_mov_b64_e32 v[54:55], 0
	v_mov_b64_e32 v[56:57], 0
	v_mov_b64_e32 v[58:59], 0
	v_mov_b64_e32 v[60:61], 0
	v_mov_b64_e32 v[62:63], 0
	v_mov_b64_e32 v[64:65], 0
	v_mov_b64_e32 v[66:67], 0
	v_mov_b64_e32 v[68:69], 0
	v_mov_b64_e32 v[70:71], 0
	v_mov_b64_e32 v[72:73], 0
	v_mov_b64_e32 v[74:75], 0
	v_mov_b64_e32 v[76:77], 0
	v_mov_b64_e32 v[78:79], 0
	v_mov_b64_e32 v[80:81], 0
	v_mov_b64_e32 v[82:83], 0
	v_mov_b64_e32 v[84:85], 0
	v_mov_b64_e32 v[86:87], 0
	v_mov_b64_e32 v[88:89], 0
	v_mov_b64_e32 v[90:91], 0
	v_mov_b64_e32 v[92:93], 0
	v_mov_b64_e32 v[94:95], 0
	v_mov_b64_e32 v[96:97], 0
	v_mov_b64_e32 v[98:99], 0
	v_mov_b64_e32 v[100:101], 0
	v_mov_b64_e32 v[102:103], 0
	v_mov_b64_e32 v[104:105], 0
	v_mov_b64_e32 v[106:107], 0
	v_mov_b64_e32 v[108:109], 0
	v_mov_b64_e32 v[110:111], 0
	v_mov_b64_e32 v[112:113], 0
	v_mov_b64_e32 v[114:115], 0
	v_mov_b64_e32 v[116:117], 0
	v_mov_b64_e32 v[118:119], 0
	v_mov_b64_e32 v[120:121], 0
	v_mov_b64_e32 v[122:123], 0
	v_mov_b64_e32 v[124:125], 0
	v_mov_b64_e32 v[126:127], 0
	.p2align	6
